# scan pass 1: end-of-chunk wait counted (vmcnt(3)); scan pass 2: finishing loop re-rolled with loads batched; Q/H fragments loaded once per chunk
# speedup vs baseline: 1.0296x; 1.0296x over previous
; __device__ __forceinline__ int crow(int r, int hi) { return (r & 3) + 8 * (r >> 2) + 4 * hi; }
; __device__ __forceinline__ void scan_pass1(const ScanP& sp, int b, int h, int seg, LAS unsigned char* lds) {
;     ...
;     f32x16 Hacc[2];
;     {
;         const int ln0 = lane & 31, hh0 = lane >> 5, cb0 = w & 1;
; #pragma unroll
;         for (int jb = 0; jb < 2; ++jb)
; #pragma unroll
;             for (int i = 0; i < 16; ++i) Hacc[jb][i] = (w >= 2 && w < 4 && (32 * jb + crow(i, hh0)) == (32 * cb0 + ln0)) ? 1.f : 0.f;
;     }
.LBB0_251:
	s_or_b64 exec, exec, s[0:1]
	s_ashr_i32 s2, s22, 6
	s_and_b32 s0, s22, 0xffffff80
	s_cmpk_eq_i32 s0, 0x80
	s_cselect_b64 s[0:1], -1, 0
	s_lshl_b32 s3, s2, 5
	v_and_b32_e32 v0, 31, v36
	v_lshrrev_b32_e32 v2, 5, v160
	s_and_b32 s82, s3, 32
	v_lshlrev_b32_e32 v3, 2, v2
	v_or_b32_e32 v19, s82, v0
	v_cmp_eq_u32_e32 vcc, v3, v19
	v_or_b32_e32 v4, 1, v3
	s_and_b64 s[4:5], s[0:1], vcc
	v_cmp_eq_u32_e32 vcc, v4, v19
	v_or_b32_e32 v4, 2, v3
	v_cndmask_b32_e64 v20, 0, 1.0, s[4:5]
	s_and_b64 s[4:5], s[0:1], vcc
	v_cmp_eq_u32_e32 vcc, v4, v19
	v_or_b32_e32 v4, 3, v3
	v_cndmask_b32_e64 v21, 0, 1.0, s[4:5]
	s_and_b64 s[4:5], s[0:1], vcc
	v_cmp_eq_u32_e32 vcc, v4, v19
	v_or_b32_e32 v4, 8, v3
	v_cndmask_b32_e64 v22, 0, 1.0, s[4:5]
	s_and_b64 s[4:5], s[0:1], vcc
	v_cmp_eq_u32_e32 vcc, v4, v19
	v_or_b32_e32 v4, 9, v3
	v_cndmask_b32_e64 v23, 0, 1.0, s[4:5]
	s_and_b64 s[4:5], s[0:1], vcc
	v_cmp_eq_u32_e32 vcc, v4, v19
	v_or_b32_e32 v4, 10, v3
	v_cndmask_b32_e64 v24, 0, 1.0, s[4:5]
	s_and_b64 s[4:5], s[0:1], vcc
	v_cmp_eq_u32_e32 vcc, v4, v19
	v_or_b32_e32 v4, 11, v3
	v_cndmask_b32_e64 v25, 0, 1.0, s[4:5]
	s_and_b64 s[4:5], s[0:1], vcc
	v_cmp_eq_u32_e32 vcc, v4, v19
	v_or_b32_e32 v4, 16, v3
	v_cndmask_b32_e64 v26, 0, 1.0, s[4:5]
	s_and_b64 s[4:5], s[0:1], vcc
	v_cmp_eq_u32_e32 vcc, v4, v19
	v_or_b32_e32 v4, 17, v3
	v_cndmask_b32_e64 v27, 0, 1.0, s[4:5]
	s_and_b64 s[4:5], s[0:1], vcc
	v_cmp_eq_u32_e32 vcc, v4, v19
	v_or_b32_e32 v4, 18, v3
	v_cndmask_b32_e64 v28, 0, 1.0, s[4:5]
	s_and_b64 s[4:5], s[0:1], vcc
	v_cmp_eq_u32_e32 vcc, v4, v19
	v_or_b32_e32 v4, 19, v3
	v_cndmask_b32_e64 v29, 0, 1.0, s[4:5]
	s_and_b64 s[4:5], s[0:1], vcc
	v_cmp_eq_u32_e32 vcc, v4, v19
	v_or_b32_e32 v4, 24, v3
	v_cndmask_b32_e64 v30, 0, 1.0, s[4:5]
	s_and_b64 s[4:5], s[0:1], vcc
	v_cmp_eq_u32_e32 vcc, v4, v19
	v_or_b32_e32 v4, 25, v3
	v_cndmask_b32_e64 v31, 0, 1.0, s[4:5]
	s_and_b64 s[4:5], s[0:1], vcc
	v_cmp_eq_u32_e32 vcc, v4, v19
	v_or_b32_e32 v4, 26, v3
	v_cndmask_b32_e64 v32, 0, 1.0, s[4:5]
	s_and_b64 s[4:5], s[0:1], vcc
	v_cmp_eq_u32_e32 vcc, v4, v19
	v_or_b32_e32 v4, 27, v3
	v_cndmask_b32_e64 v33, 0, 1.0, s[4:5]
	s_and_b64 s[4:5], s[0:1], vcc
	v_cmp_eq_u32_e32 vcc, v4, v19
	v_or_b32_e32 v4, 32, v3
	v_cndmask_b32_e64 v34, 0, 1.0, s[4:5]
	s_and_b64 s[4:5], s[0:1], vcc
	v_cmp_eq_u32_e32 vcc, v4, v19
	v_or_b32_e32 v5, 33, v3
	v_cndmask_b32_e64 v35, 0, 1.0, s[4:5]
	s_and_b64 s[4:5], s[0:1], vcc
	v_cmp_eq_u32_e32 vcc, v5, v19
	v_or_b32_e32 v6, 34, v3
	v_cndmask_b32_e64 v4, 0, 1.0, s[4:5]
	s_and_b64 s[4:5], s[0:1], vcc
	v_cmp_eq_u32_e32 vcc, v6, v19
	v_or_b32_e32 v7, 35, v3
	v_cndmask_b32_e64 v5, 0, 1.0, s[4:5]
	s_and_b64 s[4:5], s[0:1], vcc
	v_cmp_eq_u32_e32 vcc, v7, v19
	v_or_b32_e32 v8, 40, v3
	v_cndmask_b32_e64 v6, 0, 1.0, s[4:5]
	s_and_b64 s[4:5], s[0:1], vcc
	v_cmp_eq_u32_e32 vcc, v8, v19
	v_or_b32_e32 v9, 41, v3
	v_cndmask_b32_e64 v7, 0, 1.0, s[4:5]
	s_and_b64 s[4:5], s[0:1], vcc
	v_cmp_eq_u32_e32 vcc, v9, v19
	v_or_b32_e32 v10, 42, v3
	v_cndmask_b32_e64 v8, 0, 1.0, s[4:5]
	s_and_b64 s[4:5], s[0:1], vcc
	v_cmp_eq_u32_e32 vcc, v10, v19
	v_or_b32_e32 v11, 43, v3
	v_cndmask_b32_e64 v9, 0, 1.0, s[4:5]
	s_and_b64 s[4:5], s[0:1], vcc
	v_cmp_eq_u32_e32 vcc, v11, v19
	v_or_b32_e32 v12, 48, v3
	v_cndmask_b32_e64 v10, 0, 1.0, s[4:5]
	s_and_b64 s[4:5], s[0:1], vcc
	v_cmp_eq_u32_e32 vcc, v12, v19
	v_or_b32_e32 v13, 49, v3
	v_cndmask_b32_e64 v11, 0, 1.0, s[4:5]
	s_and_b64 s[4:5], s[0:1], vcc
	v_cmp_eq_u32_e32 vcc, v13, v19
	v_or_b32_e32 v14, 50, v3
	v_cndmask_b32_e64 v12, 0, 1.0, s[4:5]
	s_and_b64 s[4:5], s[0:1], vcc
	v_cmp_eq_u32_e32 vcc, v14, v19
	v_or_b32_e32 v15, 51, v3
	v_cndmask_b32_e64 v13, 0, 1.0, s[4:5]
	s_and_b64 s[4:5], s[0:1], vcc
	v_cmp_eq_u32_e32 vcc, v15, v19
	v_or_b32_e32 v16, 56, v3
	v_cndmask_b32_e64 v14, 0, 1.0, s[4:5]
	s_and_b64 s[4:5], s[0:1], vcc
	v_cmp_eq_u32_e32 vcc, v16, v19
	v_or_b32_e32 v17, 57, v3
	v_cndmask_b32_e64 v15, 0, 1.0, s[4:5]
	s_and_b64 s[4:5], s[0:1], vcc
	v_cmp_eq_u32_e32 vcc, v17, v19
; __device__ __forceinline__ int crow(int r, int hi) { return (r & 3) + 8 * (r >> 2) + 4 * hi; }
; __device__ __forceinline__ void scan_pass1(const ScanP& sp, int b, int h, int seg, LAS unsigned char* lds) {
;     ...
;         const int ln0 = lane & 31, hh0 = lane >> 5, cb0 = w & 1;
; #pragma unroll
;         for (int jb = 0; jb < 2; ++jb)
; #pragma unroll
;             for (int i = 0; i < 16; ++i) Hacc[jb][i] = (w >= 2 && w < 4 && (32 * jb + crow(i, hh0)) == (32 * cb0 + ln0)) ? 1.f : 0.f;
;     }
;     f32x4 n_cur, n_prv; u32x2 n_rc, n_kc, n_vc, n_rq, n_kq, n_vq;
;     ...
;     SCAN_PREFETCH((size_t)(tok0 + seg * 1024 + tt), (seg * 1024 + tt) > 0);
;     f32x4 r4, k4, v4, lw, kkn, kp, bb; float bon = 0.f;
	v_or_b32_e32 v18, 58, v3
	v_cndmask_b32_e64 v16, 0, 1.0, s[4:5]
	s_and_b64 s[4:5], s[0:1], vcc
	v_cmp_eq_u32_e32 vcc, v18, v19
	v_or_b32_e32 v3, 59, v3
	v_cndmask_b32_e64 v17, 0, 1.0, s[4:5]
	s_and_b64 s[4:5], s[0:1], vcc
	v_cmp_eq_u32_e32 vcc, v3, v19
	s_and_b64 s[0:1], s[0:1], vcc
	s_cmp_gt_i32 s2, 0
	s_cselect_b64 s[98:99], -1, 0
	s_lshl_b32 s3, s2, 2
	s_cmp_lt_i32 s2, 4
	s_cselect_b64 s[88:89], -1, 0
	s_cmp_gt_i32 s2, 3
	s_cselect_b64 s[56:57], -1, 0
	s_add_i32 s8, s2, -4
	v_cndmask_b32_e64 v19, 0, 1.0, s[0:1]
	v_readlane_b32 s0, v254, 22
	s_cmp_eq_u32 s8, 2
	v_cndmask_b32_e64 v18, 0, 1.0, s[4:5]
	v_add_u32_e32 v165, s0, v122
	s_cselect_b64 s[0:1], -1, 0
	s_and_b64 s[4:5], s[0:1], exec
	s_mov_b32 s4, 0x10e00
	s_cselect_b32 s9, s4, 0x12200
	s_cmp_eq_u32 s8, 0
	s_cselect_b64 s[4:5], -1, 0
	s_and_b64 s[6:7], s[4:5], exec
	s_cselect_b32 s6, 0x10400, s9
	s_or_b64 s[0:1], s[4:5], s[0:1]
	s_and_b64 s[0:1], s[0:1], exec
	s_mov_b32 s0, 0xa400
	s_cselect_b32 s0, s0, 0xb600
	s_cmp_lt_u32 s2, 6
	s_mov_b32 s1, 0x9200
	s_cselect_b32 s1, 0x8000, s1
	s_add_i32 s65, s0, 0
	s_add_i32 s77, s1, 0
	s_cmp_lg_u32 s8, 1
	v_mul_lo_u32 v43, v38, s72
	s_cselect_b64 s[72:73], -1, 0
	s_cmp_eq_u32 s8, 3
	v_readlane_b32 s0, v254, 23
	s_cselect_b64 s[74:75], -1, 0
	s_add_i32 s33, s6, 0
	v_add_u32_e32 v167, s0, v122
	s_add_i32 s0, 0, 0x17f00
	v_add_u32_e32 v168, s0, v122
	s_add_i32 s0, 0, 0x18000
	v_add_u32_e32 v169, s0, v122
	v_readlane_b32 s0, v254, 24
	s_lshl_b32 s92, s2, 10
	v_add_lshl_u32 v163, v43, v39, 1
	v_add_u32_e32 v170, s0, v122
	v_readlane_b32 s0, v254, 25
	v_mul_u32_u24_e32 v39, 0xa0, v37
	s_cmp_gt_i32 s2, 1
	v_add_u32_e32 v171, s0, v122
	v_readlane_b32 s0, v254, 26
	v_lshlrev_b32_e32 v3, 1, v38
	v_lshlrev_b32_e32 v39, 1, v39
	v_add_u32_e32 v173, s0, v122
	v_readlane_b32 s0, v254, 27
	s_cselect_b64 s[62:63], -1, 0
	s_cmp_lt_i32 s2, 2
	v_add_u32_e32 v175, s0, v122
	v_readlane_b32 s0, v254, 28
	v_add3_u32 v164, 0, v3, v39
	s_movk_i32 s1, 0x48
	v_and_or_b32 v3, v36, 3, s3
	v_add_u32_e32 v176, s0, v122
	v_readlane_b32 s0, v254, 29
	s_cselect_b64 s[54:55], -1, 0
	v_readlane_b32 s24, v254, 20
	v_readlane_b32 s25, v254, 21
	v_mul_lo_u32 v42, v36, 48
	v_mul_lo_u32 v3, v3, s1
	v_lshrrev_b32_e32 v36, 4, v160
	v_add_u32_e32 v177, s0, v122
	s_and_b64 s[0:1], s[54:55], exec
	v_or_b32_e32 v36, s3, v36
	s_cselect_b32 s80, s24, s25
	s_or_b32 s0, s3, 2
	v_add_u32_e32 v40, s24, v122
	v_add_u32_e32 v41, s25, v122
	v_lshlrev_b32_e32 v36, 8, v36
	v_cmp_le_i32_e64 s[16:17], s0, v38
	s_lshl_b32 s81, s0, 8
	s_or_b32 s0, s3, 3
	v_add_u32_e32 v172, v40, v36
	v_add_u32_e32 v174, v41, v36
	v_cmp_le_i32_e64 s[18:19], s0, v38
	s_lshl_b32 s20, s0, 8
	s_add_i32 s0, s24, s92
	v_lshlrev_b32_e32 v36, 2, v0
	v_add_u32_e32 v181, s0, v36
	s_add_i32 s0, s25, s92
	v_add_u32_e32 v182, s0, v36
	s_lshl_b32 s0, s23, 2
	s_add_u32 s94, s39, s0
	s_addc_u32 s95, s41, 0
	s_cmp_lg_u32 s2, 1
	v_writelane_b32 v252, s0, 11
	s_cselect_b64 s[58:59], -1, 0
	s_and_b32 s64, s2, 0x7ffffffe
	v_readlane_b32 s0, v254, 40
	v_lshlrev_b32_e32 v2, 3, v2
	v_mul_u32_u24_e32 v0, 40, v0
	s_bitcmp1_b32 s22, 6
	v_readlane_b32 s1, v254, 41
	v_add_lshl_u32 v3, v3, v2, 1
	v_lshlrev_b32_e32 v178, 8, v38
	v_cmp_le_i32_e64 s[12:13], s3, v38
	v_cmp_lt_i32_e64 s[14:15], s3, v38
	v_add_lshl_u32 v0, v2, v0, 1
	v_mov_b32_e32 v123, v1
	s_cselect_b64 s[2:3], -1, 0
	v_lshl_add_u64 v[128:129], s[0:1], 0, v[120:121]
	s_add_i32 s0, 0, 0x6000
	v_add_u32_e32 v162, 0, v122
	v_cmp_eq_u32_e64 s[52:53], 31, v38
	v_cndmask_b32_e64 v166, 0, 1, s[4:5]
	v_cmp_gt_u32_e64 s[6:7], 8, v37
	v_cmp_gt_u32_e64 s[8:9], 32, v160
	v_add_u32_e32 v179, v40, v178
	v_add_u32_e32 v180, v41, v178
	v_cmp_eq_u32_e64 s[10:11], 0, v37
	v_lshl_add_u64 v[124:125], s[84:85], 0, v[122:123]
	v_lshl_add_u64 v[126:127], s[42:43], 0, v[120:121]
	v_lshl_add_u32 v183, v37, 4, s0
	s_mov_b32 s83, -1
	v_mov_b32_e32 v187, 0
	v_add_u32_e32 v184, 0, v42
	v_add_u32_e32 v185, 0, v3
	v_add_u32_e32 v186, 0, v0
	s_waitcnt vmcnt(0)

; #define LAS __attribute__((address_space(3)))
; __device__ __forceinline__ unsigned pk2(float lo, float hi) { f32x2 v = {lo, hi}; bf16x2_t b = __builtin_convertvector(v, bf16x2_t); return __builtin_bit_cast(unsigned, b); }
; __device__ __forceinline__ void scan_pass1(const ScanP& sp, int b, int h, int seg, LAS unsigned char* lds) {
;     ...
;         {
;             const f32x4 cur = n_cur, prv = n_prv;
;             f32x4 s = cur + (prv - cur) * PARV(3);
;             if (jg < 8) {
; #pragma unroll
;                 for (int e = 0; e < 4; ++e) s[e] = 1.0f - 2.0f * __builtin_amdgcn_rcpf(1.0f + __expf(2.0f * s[e]));
;             }
;             { u32x2 o_; o_.x = pk2(s[0], s[1]); o_.y = pk2(s[2], s[3]); *(LAS u32x2*)(lds + O_LORA + (tt * 72 + j4) * 2) = o_; }
;         }
.LBB0_286:
	s_add_i32 s22, s83, 1
	s_cmp_eq_u32 s83, 31
	s_cbranch_scc1 .LBB0_300
	ds_read_b128 v[68:71], v167
	s_waitcnt lgkmcnt(0)
	v_sub_f32_e32 v73, v89, v85
	v_sub_f32_e32 v72, v88, v84
	v_sub_f32_e32 v3, v91, v87
	v_sub_f32_e32 v2, v90, v86
	v_pk_fma_f32 v[2:3], v[2:3], v[70:71], v[86:87]
	v_pk_fma_f32 v[68:69], v[72:73], v[68:69], v[84:85]
	s_and_saveexec_b64 s[0:1], s[6:7]
	s_cbranch_execz .LBB0_289
	v_add_f32_e32 v0, v68, v68
	v_mul_f32_e32 v0, 0x3fb8aa3b, v0
	v_exp_f32_e32 v0, v0
	v_add_f32_e32 v68, v69, v69
	v_mul_f32_e32 v68, 0x3fb8aa3b, v68
	v_exp_f32_e32 v69, v68
	v_add_f32_e32 v0, 1.0, v0
	v_rcp_f32_e32 v68, v0
	v_add_f32_e32 v0, v2, v2
	v_mul_f32_e32 v0, 0x3fb8aa3b, v0
	v_add_f32_e32 v2, v3, v3
	v_exp_f32_e32 v0, v0
	v_mul_f32_e32 v2, 0x3fb8aa3b, v2
	v_exp_f32_e32 v3, v2
	v_add_f32_e32 v69, 1.0, v69
	v_add_f32_e32 v0, 1.0, v0
	v_rcp_f32_e32 v2, v0
	v_add_f32_e32 v0, 1.0, v3
	v_rcp_f32_e32 v3, v0
	v_rcp_f32_e32 v69, v69
	v_pk_fma_f32 v[2:3], v[2:3], -2.0, 1.0 op_sel_hi:[1,0,0]
	v_pk_fma_f32 v[68:69], v[68:69], -2.0, 1.0 op_sel_hi:[1,0,0]

; #define LAS __attribute__((address_space(3)))
; __device__ __forceinline__ void scan_pass1(const ScanP& sp, int b, int h, int seg, LAS unsigned char* lds) {
;     ...
;         {
;             const u32x2 rc = n_rc, kc = n_kc, vc = n_vc, rq = n_rq, kq = n_kq, vq = n_vq;
;             const f32x4 rcf = {bflo(rc.x), bfhi(rc.x), bflo(rc.y), bfhi(rc.y)}, rqf = {bflo(rq.x), bfhi(rq.x), bflo(rq.y), bfhi(rq.y)};
;             const f32x4 kcf = {bflo(kc.x), bfhi(kc.x), bflo(kc.y), bfhi(kc.y)}, kqf = {bflo(kq.x), bfhi(kq.x), bflo(kq.y), bfhi(kq.y)};
;             const f32x4 vcf = {bflo(vc.x), bfhi(vc.x), bflo(vc.y), bfhi(vc.y)}, vqf = {bflo(vq.x), bfhi(vq.x), bflo(vq.y), bfhi(vq.y)};
;             r4 = rcf + (rqf - rcf) * PARV(0); k4 = kcf + (kqf - kcf) * PARV(1); v4 = vcf + (vqf - vcf) * PARV(2);
;         }
;         if (chunk + 1 < 32) SCAN_PREFETCH(tok + 32, 1);
;         asm volatile("s_waitcnt lgkmcnt(0)" ::: "memory");
;         bon = 0.f;
;         {
;             f32x4 wacc, aacc;
;             {
;                 const int l5_ = lane & 31, h5_ = lane >> 5;
;                 const LAS unsigned char* arow = lds + O_LORA + ((4 * w + (l5_ & 3)) * 72 + h5_ * 8) * 2;
; #pragma unroll
;                 for (int lo_ = 0; lo_ < 2; ++lo_)
; #pragma unroll
;                     for (int jb_ = 0; jb_ < 2; ++jb_) {
;                         f32x16 D_;
; #pragma unroll
;                         for (int i = 0; i < 16; ++i) D_[i] = 0.f;
; #pragma unroll
;                         for (int ks = 0; ks < 2; ++ks)
;                             D_ = MFMA32(*(const LAS bf16x8*)(arow + (lo_ * 32 + ks * 16) * 2), *(const LAS bf16x8*)(lds + O_WUP + lo_ * 5120 + ((32 * jb_ + l5_) * 40 + ks * 16 + h5_ * 8) * 2), D_);
;                         if (h5_ == 0) {
;                             LAS float* dst_ = (lo_ == 0 ? yb : qb) + (w * 4) * 64 + 32 * jb_ + l5_;
;                             dst_[0] = D_[0]; dst_[64] = D_[1]; dst_[128] = D_[2]; dst_[192] = D_[3];
;                         }
;                     }
;                 asm volatile("s_waitcnt lgkmcnt(0)" ::: "memory");
;                 wacc = PARV(4) + *(const LAS f32x4*)(yb + (w * 4 + (lane >> 4)) * 64 + j4);
;                 aacc = PARV(5) + *(const LAS f32x4*)(qb + (w * 4 + (lane >> 4)) * 64 + j4);
;             }
;             float ssq = 0.f; f32x4 av;
; #pragma unroll
;             for (int e = 0; e < 4; ++e) {
.LBB0_299:
	s_or_b64 exec, exec, s[0:1]
	s_nop 8
	v_lshlrev_b32_e32 v68, 16, v142
	v_and_b32_e32 v69, 0xffff0000, v142
	v_lshlrev_b32_e32 v70, 16, v143
	v_and_b32_e32 v71, 0xffff0000, v143
	v_lshlrev_b32_e32 v0, 16, v144
	v_and_b32_e32 v76, 0xffff0000, v144
	v_lshlrev_b32_e32 v78, 16, v145
	v_and_b32_e32 v79, 0xffff0000, v145
	v_lshlrev_b32_e32 v72, 16, v140
	v_and_b32_e32 v73, 0xffff0000, v140
	v_lshlrev_b32_e32 v74, 16, v141
	v_and_b32_e32 v75, 0xffff0000, v141
	v_lshlrev_b32_e32 v112, 16, v148
	v_and_b32_e32 v113, 0xffff0000, v148
	v_lshlrev_b32_e32 v114, 16, v149
	v_and_b32_e32 v115, 0xffff0000, v149
	v_sub_f32_e32 v77, v76, v69
	v_sub_f32_e32 v76, v0, v68
	v_sub_f32_e32 v79, v79, v71
	v_sub_f32_e32 v78, v78, v70
	v_pk_fma_f32 v[70:71], v[78:79], v[110:111], v[70:71]
	v_pk_fma_f32 v[68:69], v[76:77], v[108:109], v[68:69]
	v_sub_f32_e32 v79, v113, v73
	v_sub_f32_e32 v78, v112, v72
	v_sub_f32_e32 v77, v115, v75
	v_sub_f32_e32 v76, v114, v74
	s_waitcnt lgkmcnt(0)
	v_pk_fma_f32 v[76:77], v[76:77], v[106:107], v[74:75]
	v_pk_fma_f32 v[78:79], v[78:79], v[104:105], v[72:73]
	ds_read_b128 v[104:107], v171
	ds_read_b128 v[108:111], v172
	v_lshlrev_b32_e32 v80, 16, v138
	v_and_b32_e32 v81, 0xffff0000, v138
	v_lshlrev_b32_e32 v116, 16, v146
	v_and_b32_e32 v117, 0xffff0000, v146
	s_waitcnt lgkmcnt(0)
	v_add_f32_e32 v0, v104, v108
	v_mul_f32_e64 v104, |v0|, s40
	v_exp_f32_e32 v104, v104
	v_sub_f32_e32 v73, v117, v81
	v_sub_f32_e32 v72, v116, v80
	v_pk_fma_f32 v[72:73], v[72:73], v[100:101], v[80:81]
	v_add_f32_e32 v80, 1.0, v104
	v_cmp_gt_f32_e32 vcc, s78, v80
	v_max_f32_e64 v0, -v0, 0
	v_lshlrev_b32_e32 v82, 16, v139
	v_cndmask_b32_e64 v81, 0, 32, vcc
	v_ldexp_f32 v80, v80, v81
	v_log_f32_e32 v80, v80
	v_and_b32_e32 v83, 0xffff0000, v139
	v_lshlrev_b32_e32 v118, 16, v147
	v_and_b32_e32 v119, 0xffff0000, v147
	v_mul_f32_e32 v81, 0x3f317217, v80
	v_fma_f32 v81, v80, s79, -v81
	v_fmac_f32_e32 v81, 0x3377d1cf, v80
	v_fmac_f32_e32 v81, 0x3f317217, v80
	v_cmp_lt_f32_e64 s[0:1], |v80|, s37
	v_sub_f32_e32 v75, v119, v83
	v_sub_f32_e32 v74, v118, v82
	v_cndmask_b32_e64 v80, v80, v81, s[0:1]
	v_cndmask_b32_e32 v81, 0, v218, vcc
	v_sub_f32_e32 v80, v80, v81
	v_add_f32_e32 v0, v0, v80
	v_sub_f32_e32 v0, -0.5, v0
	v_mul_f32_e32 v0, 0x3fb8aa3b, v0
	v_exp_f32_e32 v80, v0
	v_add_f32_e32 v0, v105, v109
	v_mul_f32_e64 v81, |v0|, s40
	v_exp_f32_e32 v81, v81
	v_pk_fma_f32 v[74:75], v[74:75], v[102:103], v[82:83]
	ds_read_b128 v[112:115], v173
	ds_read_b128 v[116:119], v174
	ds_read_b128 v[100:103], v175
	v_add_f32_e32 v81, 1.0, v81
	v_cmp_gt_f32_e32 vcc, s78, v81
	v_max_f32_e64 v0, -v0, 0
	v_add_f32_e32 v106, v106, v110
	v_cndmask_b32_e64 v83, 0, 32, vcc
	v_ldexp_f32 v81, v81, v83
	v_log_f32_e32 v81, v81
	s_waitcnt lgkmcnt(0)
; #define LAS __attribute__((address_space(3)))
; __device__ __forceinline__ float red16(float v) { v = red8(v); v += __int_as_float(__builtin_amdgcn_update_dpp(0, __float_as_int(v), 0x140, 0xF, 0xF, true)); return v; }
; __device__ __forceinline__ void scan_pass1(const ScanP& sp, int b, int h, int seg, LAS unsigned char* lds) {
;     ...
;             float ssq = 0.f; f32x4 av;
; #pragma unroll
;             for (int e = 0; e < 4; ++e) {
;                 const float xw = -wacc[e]; const float spv = fmaxf(xw, 0.f) + __logf(1.0f + __expf(-fabsf(xw)));
;                 lw[e] = -__expf(-spv - 0.5f) * LOG2E;
;                 av[e] = __builtin_amdgcn_rcpf(1.0f + __expf(-aacc[e]));
;                 kkn[e] = k4[e] * PARV(6)[e]; ssq += kkn[e] * kkn[e];
;             }
;             ssq = red16(ssq);
;             const float inrm = __builtin_amdgcn_rsqf(fmaxf(ssq, 1e-24f));
; #pragma unroll
;             for (int e = 0; e < 4; ++e) {
;                 kkn[e] *= inrm; kp[e] = k4[e] * (1.0f + (av[e] - 1.0f) * PARV(7)[e]); bb[e] = kkn[e] * av[e];
;                 bon += r4[e] * kp[e] * PARV(8)[e];
;             }
;             bon = red16(bon);
;             *(LAS f32x4*)(lwS + tt * 64 + j4) = lw;
;             *(LAS f32x4*)(stash + tid * 12) = r4; *(LAS f32x4*)(stash + tid * 12 + 4) = v4; *(LAS f32x4*)(stash + tid * 12 + 8) = kp;
	v_pk_mul_f32 v[104:105], v[78:79], v[100:101]
	v_pk_mul_f32 v[100:101], v[76:77], v[102:103]
	v_add_f32_e32 v82, v112, v116
	v_mul_f32_e32 v83, 0x3f317217, v81
	v_fma_f32 v83, v81, s79, -v83
	v_fmac_f32_e32 v83, 0x3377d1cf, v81
	v_fmac_f32_e32 v83, 0x3f317217, v81
	v_cmp_lt_f32_e64 s[0:1], |v81|, s37
	v_mul_f32_e32 v82, 0xbfb8aa3b, v82
	v_exp_f32_e32 v82, v82
	v_cndmask_b32_e64 v81, v81, v83, s[0:1]
	v_cndmask_b32_e32 v83, 0, v218, vcc
	v_sub_f32_e32 v81, v81, v83
	v_add_f32_e32 v0, v0, v81
	v_add_f32_e32 v81, v113, v117
	v_mul_f32_e32 v81, 0xbfb8aa3b, v81
	v_exp_f32_e32 v83, v81
	v_sub_f32_e32 v0, -0.5, v0
	v_mul_f32_e32 v0, 0x3fb8aa3b, v0
	v_exp_f32_e32 v81, v0
	v_add_f32_e32 v0, 1.0, v83
	v_mul_f32_e64 v83, |v106|, s40
	v_exp_f32_e32 v108, v83
	v_rcp_f32_e32 v83, v0
	v_pk_mul_f32 v[112:113], v[104:105], v[104:105]
	v_add_f32_e32 v82, 1.0, v82
	v_add_f32_e32 v0, 1.0, v108
	v_cmp_gt_f32_e32 vcc, s78, v0
	v_pk_mul_f32 v[108:109], v[100:101], v[100:101]
	v_rcp_f32_e32 v82, v82
	v_cndmask_b32_e64 v102, 0, 32, vcc
	v_ldexp_f32 v0, v0, v102
	v_log_f32_e32 v0, v0
	v_max_f32_e64 v102, -v106, 0
	v_add_f32_e32 v106, v114, v118
	v_mul_f32_e32 v106, 0xbfb8aa3b, v106
	v_mul_f32_e32 v103, 0x3f317217, v0
	v_fma_f32 v103, v0, s79, -v103
	v_fmac_f32_e32 v103, 0x3377d1cf, v0
	v_fmac_f32_e32 v103, 0x3f317217, v0
	v_cmp_lt_f32_e64 s[0:1], |v0|, s37
	v_exp_f32_e32 v106, v106
	s_nop 0
	v_cndmask_b32_e64 v0, v0, v103, s[0:1]
	v_cndmask_b32_e32 v103, 0, v218, vcc
	v_sub_f32_e32 v0, v0, v103
	v_add_f32_e32 v0, v102, v0
	v_sub_f32_e32 v0, -0.5, v0
	v_mul_f32_e32 v0, 0x3fb8aa3b, v0
	v_exp_f32_e32 v102, v0
	v_add_f32_e32 v0, v107, v111
	v_mul_f32_e64 v103, |v0|, s40
	v_exp_f32_e32 v103, v103
	v_max_f32_e64 v0, -v0, 0
	v_add_f32_e32 v106, 1.0, v106
	v_rcp_f32_e32 v106, v106
	v_add_f32_e32 v103, 1.0, v103
	v_cmp_gt_f32_e32 vcc, s78, v103
	s_nop 1
	v_cndmask_b32_e64 v107, 0, 32, vcc
	v_ldexp_f32 v103, v103, v107
	v_log_f32_e32 v103, v103
	s_nop 0
	v_mul_f32_e32 v107, 0x3f317217, v103
	v_fma_f32 v107, v103, s79, -v107
	v_fmac_f32_e32 v107, 0x3377d1cf, v103
	v_fmac_f32_e32 v107, 0x3f317217, v103
	v_cmp_lt_f32_e64 s[0:1], |v103|, s37
	s_nop 1
	v_cndmask_b32_e64 v103, v103, v107, s[0:1]
	v_cndmask_b32_e32 v107, 0, v218, vcc
	v_sub_f32_e32 v103, v103, v107
	v_add_f32_e32 v0, v0, v103
	v_add_f32_e32 v103, v115, v119
	v_sub_f32_e32 v0, -0.5, v0
	v_mul_f32_e32 v103, 0xbfb8aa3b, v103
	v_mul_f32_e32 v0, 0x3fb8aa3b, v0
	v_exp_f32_e32 v107, v103
	v_exp_f32_e32 v103, v0
	v_add_f32_e32 v0, v112, v113
	v_add_f32_e32 v0, v108, v0
	v_add_f32_e32 v0, v109, v0
	ds_read_b128 v[108:111], v176
	ds_read_b128 v[112:115], v177
	v_add_f32_dpp v0, v0, v0 quad_perm:[1,0,3,2] row_mask:0xf bank_mask:0xf bound_ctrl:1
	v_add_f32_e32 v107, 1.0, v107
	v_rcp_f32_e32 v107, v107
	v_add_f32_dpp v0, v0, v0 quad_perm:[2,3,0,1] row_mask:0xf bank_mask:0xf bound_ctrl:1
	v_pk_mul_f32 v[102:103], v[102:103], s[40:41] op_sel_hi:[1,0]
	s_nop 0
	v_add_f32_dpp v0, v0, v0 row_half_mirror row_mask:0xf bank_mask:0xf bound_ctrl:1
	s_nop 1
	v_add_f32_dpp v0, v0, v0 row_mirror row_mask:0xf bank_mask:0xf bound_ctrl:1
	v_max_f32_e32 v0, 0x179abe15, v0
	v_rsq_f32_e32 v0, v0
	s_nop 0
	v_pk_mul_f32 v[130:131], v[104:105], v[0:1] op_sel_hi:[1,0]
	v_pk_add_f32 v[104:105], v[82:83], -1.0 op_sel_hi:[1,0]
	v_pk_mul_f32 v[132:133], v[100:101], v[0:1] op_sel_hi:[1,0]
	s_waitcnt lgkmcnt(0)
	v_pk_fma_f32 v[104:105], v[104:105], v[108:109], 1.0 op_sel_hi:[1,1,0]
	v_pk_mul_f32 v[136:137], v[106:107], v[132:133]
	v_pk_mul_f32 v[104:105], v[78:79], v[104:105]
	v_pk_mul_f32 v[134:135], v[82:83], v[130:131]
	v_pk_mul_f32 v[78:79], v[68:69], v[104:105]
	v_pk_mul_f32 v[100:101], v[80:81], s[40:41] op_sel_hi:[1,0]
	v_pk_mul_f32 v[78:79], v[112:113], v[78:79]
	s_nop 0
	v_add_f32_e32 v78, 0, v78
	v_add_f32_e32 v108, v79, v78
	v_pk_add_f32 v[78:79], v[106:107], -1.0 op_sel_hi:[1,0]
	s_nop 0
	v_pk_fma_f32 v[78:79], v[78:79], v[110:111], 1.0 op_sel_hi:[1,1,0]
	s_nop 0
	v_pk_mul_f32 v[106:107], v[76:77], v[78:79]
	s_nop 0
	v_pk_mul_f32 v[76:77], v[70:71], v[106:107]
	s_nop 0
	v_pk_mul_f32 v[76:77], v[114:115], v[76:77]
	s_nop 0
	v_add_f32_e32 v0, v76, v108
	v_add_f32_e32 v0, v77, v0
	v_add_u32_e32 v76, v162, v178
	ds_write_b128 v76, v[100:103] offset:24576
	ds_write_b128 v190, v[68:71]
	ds_write_b128 v190, v[72:75] offset:16
	ds_write_b128 v190, v[104:107] offset:32
	v_add_f32_dpp v0, v0, v0 quad_perm:[1,0,3,2] row_mask:0xf bank_mask:0xf bound_ctrl:1
	s_nop 1
	v_add_f32_dpp v0, v0, v0 quad_perm:[2,3,0,1] row_mask:0xf bank_mask:0xf bound_ctrl:1
	s_nop 1
	v_add_f32_dpp v0, v0, v0 row_half_mirror row_mask:0xf bank_mask:0xf bound_ctrl:1
	s_nop 1
	v_add_f32_dpp v0, v0, v0 row_mirror row_mask:0xf bank_mask:0xf bound_ctrl:1
	s_andn2_b64 vcc, exec, s[70:71]
	s_cbranch_vccz .LBB0_301
	s_waitcnt vmcnt(0)
	s_branch .LBB0_318

; __device__ __forceinline__ void scan_pass1(const ScanP& sp, int b, int h, int seg, LAS unsigned char* lds) {
;     ...
;     for (int ci = -1; ci < 32; ++ci) {
;     ...
;         if (chunk + 1 < 32) SCAN_PREFETCH(tok + 32, 1);
.LBB0_318:
	s_cmp_eq_u32 s22, 32
	s_cbranch_scc1 .LBB0_320
	s_waitcnt vmcnt(3)
	v_mov_b64_e32 v[142:143], v[2:3]
	v_mov_b64_e32 v[140:141], v[150:151]
	v_mov_b64_e32 v[138:139], v[152:153]
	v_mov_b64_e32 v[144:145], v[154:155]
	v_mov_b64_e32 v[148:149], v[156:157]
	v_mov_b64_e32 v[146:147], v[158:159]
	v_mov_b32_e32 v187, v0
	s_mov_b32 s83, s22
	s_branch .LBB0_252

; #define LAS __attribute__((address_space(3)))
; #define MFMA32(a, b, c) __builtin_amdgcn_mfma_f32_32x32x16_bf16((a), (b), (c), 0, 0, 0)
; __device__ __forceinline__ int crow(int r, int hi) { return (r & 3) + 8 * (r >> 2) + 4 * hi; }
; __device__ __forceinline__ void scan_pass2(const ScanP& sp, int b, int h, int seg, LAS unsigned char* lds) {
;     ...
;     for (int c = w; c < 32; c += 8) {
;         const int t0 = seg * 1024 + c * 32;
; #pragma unroll
;         for (int ib = 0; ib < 2; ++ib) {
;             f32x16 acc;
; #pragma unroll
;             for (int i = 0; i < 16; ++i) acc[i] = 0.f;
; #pragma unroll
;             for (int ks = 0; ks < 4; ++ks) {
;                 const bf16x8 qa = *(const bf16x8*)(sp.Q + (size_t)(tok0 + t0 + ln) * 512 + h * 64 + ks * 16 + hh * 8);
;                 const bf16x8 hb = *(const LAS bf16x8*)(HiT + ((ib * 32 + ln) * 72 + ks * 16 + hh * 8) * 2);
;                 acc = MFMA32(qa, hb, acc);
;             }
; #pragma unroll
;             for (int r = 0; r < 16; ++r) ybw[crow(r, hh) * 64 + ib * 32 + ln] = acc[r];
;         }
.LBB0_342:
	s_lshl_b32 s2, s4, 5
	s_add_i32 s2, s2, s5
	v_add_u32_e32 v2, s2, v19
	v_ashrrev_i32_e32 v3, 31, v2
	v_lshlrev_b64 v[2:3], 10, v[2:3]
	v_lshl_add_u64 v[24:25], v[20:21], 0, v[2:3]
	global_load_dwordx4 v[130:133], v[24:25], off
	global_load_dwordx4 v[134:137], v[24:25], off offset:32
	global_load_dwordx4 v[138:141], v[24:25], off offset:64
	global_load_dwordx4 v[142:145], v[24:25], off offset:96
	ds_read_b128 v[146:149], v30 offset:32768
	ds_read_b128 v[150:153], v30 offset:32800
	ds_read_b128 v[154:157], v30 offset:32832
	ds_read_b128 v[158:161], v30 offset:32864
	ds_read_b128 v[162:165], v30 offset:37376
	ds_read_b128 v[166:169], v30 offset:37408
	ds_read_b128 v[170:173], v30 offset:37440
	ds_read_b128 v[174:177], v30 offset:37472
	s_mov_b32 s6, 0
	s_waitcnt vmcnt(0) lgkmcnt(0)
	v_mfma_f32_32x32x16_bf16 v[2:17], v[130:133], v[146:149], 0
	v_mfma_f32_32x32x16_bf16 v[178:193], v[130:133], v[162:165], 0
	v_mfma_f32_32x32x16_bf16 v[2:17], v[134:137], v[150:153], v[2:17]
	v_mfma_f32_32x32x16_bf16 v[178:193], v[134:137], v[166:169], v[178:193]
	v_mfma_f32_32x32x16_bf16 v[2:17], v[138:141], v[154:157], v[2:17]
	v_mfma_f32_32x32x16_bf16 v[178:193], v[138:141], v[170:173], v[178:193]
	v_mfma_f32_32x32x16_bf16 v[2:17], v[142:145], v[158:161], v[2:17]
	v_mfma_f32_32x32x16_bf16 v[178:193], v[142:145], v[174:177], v[178:193]
	v_mov_b32_e32 v32, v29
	s_nop 11
	ds_write_b32 v31, v2 offset:43008
	ds_write_b32 v31, v3 offset:43264
	ds_write_b32 v31, v4 offset:43520
	ds_write_b32 v31, v5 offset:43776
	ds_write_b32 v31, v6 offset:45056
	ds_write_b32 v31, v7 offset:45312
	ds_write_b32 v31, v8 offset:45568
	ds_write_b32 v31, v9 offset:45824
	ds_write_b32 v31, v10 offset:47104
	ds_write_b32 v31, v11 offset:47360
	ds_write_b32 v31, v12 offset:47616
	ds_write_b32 v31, v13 offset:47872
	ds_write_b32 v31, v14 offset:49152
	ds_write_b32 v31, v15 offset:49408
	ds_write_b32 v31, v16 offset:49664
	ds_write_b32 v31, v17 offset:49920
	ds_write_b32 v31, v178 offset:43136
	ds_write_b32 v31, v179 offset:43392
	ds_write_b32 v31, v180 offset:43648
	ds_write_b32 v31, v181 offset:43904
	ds_write_b32 v31, v182 offset:45184
	ds_write_b32 v31, v183 offset:45440
	ds_write_b32 v31, v184 offset:45696
	ds_write_b32 v31, v185 offset:45952
	ds_write_b32 v31, v186 offset:47232
	ds_write_b32 v31, v187 offset:47488
	ds_write_b32 v31, v188 offset:47744
	ds_write_b32 v31, v189 offset:48000
	ds_write_b32 v31, v190 offset:49280
	ds_write_b32 v31, v191 offset:49536
	ds_write_b32 v31, v192 offset:49792
	ds_write_b32 v31, v193 offset:50048
	s_waitcnt lgkmcnt(0)
	s_branch .LBB0_344
; #define LAS __attribute__((address_space(3)))
; __device__ __forceinline__ unsigned pk2(float lo, float hi) { f32x2 v = {lo, hi}; bf16x2_t b = __builtin_convertvector(v, bf16x2_t); return __builtin_bit_cast(unsigned, b); }
; __device__ __forceinline__ float bflo(unsigned u) { return __uint_as_float(u << 16); }
; __device__ __forceinline__ float bfhi(unsigned u) { return __uint_as_float(u & 0xffff0000u); }
; __device__ __forceinline__ float silu(float g) { return g * __builtin_amdgcn_rcpf(1.0f + __expf(-g)); }
; __device__ __forceinline__ void scan_pass2(const ScanP& sp, int b, int h, int seg, LAS unsigned char* lds) {
;     ...
; #pragma unroll 4
;         for (int it = 0; it < 8; ++it) {
;             const int item = it * 64 + lane, tt = item >> 4, jg = item & 15, j4 = 4 * jg, ch = h * 64 + j4;
;             const int t = t0 + tt; const size_t tok = (size_t)(tok0 + t);
;             const u32x2 y0 = *(const u32x2*)(sp.mixed + tok * 1024 + 512 + ch);
;             const f32x4 dy = *(const LAS f32x4*)(ybw + tt * 64 + j4);
;             const f32x4 y = {bflo(y0.x) + dy[0], bfhi(y0.x) + dy[1], bflo(y0.y) + dy[2], bfhi(y0.y) + dy[3]};
;             const float mean = red16((y[0] + y[1]) + (y[2] + y[3])) * (1.0f / 64.0f);
;             const f32x4 dlt = y - mean;
;             const float var = red16((dlt[0] * dlt[0] + dlt[1] * dlt[1]) + (dlt[2] * dlt[2] + dlt[3] * dlt[3])) * (1.0f / 64.0f);
;             const float rs = __builtin_amdgcn_rsqf(var + 64e-5f);
;             const bf16_t* vp = sp.P + tok * PP + 3072 + ch;
;             const u32x2 vc = *(const u32x2*)vp; u32x2 vq = {0u, 0u}; if (t > 0) vq = *(const u32x2*)(vp - PP);
;             const f32x4 vcf = {bflo(vc.x), bfhi(vc.x), bflo(vc.y), bfhi(vc.y)}, vqf = {bflo(vq.x), bfhi(vq.x), bflo(vq.y), bfhi(vq.y)};
;             const f32x4 v4 = vcf + (vqf - vcf) * *(const LAS f32x4*)(par + j4);
;             const float bon = sp.bon[tok * 8 + h];
;             const u32x2 gr = *(const u32x2*)(sp.P + tok * PP + 3584 + ch);
;             const f32x4 yo = dlt * rs * *(const LAS f32x4*)(par + 64 + j4) + *(const LAS f32x4*)(par + 128 + j4) + v4 * bon;
;             u32x2 o; o.x = pk2(yo[0] * silu(bflo(gr.x)), yo[1] * silu(bfhi(gr.x))); o.y = pk2(yo[2] * silu(bflo(gr.y)), yo[3] * silu(bfhi(gr.y)));
;             *(u32x2*)(sp.mixed + tok * 1024 + 512 + ch) = o;
;         }
.LBB0_344:
	v_add_u32_e32 v2, s6, v28
	v_ashrrev_i32_e32 v3, 31, v2
	v_lshlrev_b64 v[4:5], 11, v[2:3]
	v_lshl_add_u64 v[6:7], v[22:23], 0, v[4:5]
	global_load_dwordx2 v[4:5], v[6:7], off offset:1024
	ds_read_b128 v[8:11], v32
	v_add_u32_e32 v33, s6, v27
	v_mov_b32_e32 v16, 0
	v_mov_b32_e32 v17, 0
	v_mov_b64_e32 v[12:13], s[68:69]
	v_mad_i64_i32 v[12:13], s[2:3], v2, s76, v[12:13]
	v_lshlrev_b32_e32 v0, 1, v18
	v_lshl_add_u64 v[12:13], v[12:13], 0, v[0:1]
	v_add_co_u32_e32 v14, vcc, 0x1000, v12
	s_nop 1
	v_addc_co_u32_e32 v15, vcc, 0, v13, vcc
	global_load_dwordx2 v[100:101], v[14:15], off offset:2048
	v_cmp_lt_i32_e32 vcc, 0, v33
	s_and_saveexec_b64 s[2:3], vcc
	v_lshl_add_u64 v[16:17], v[12:13], 0, s[60:61]
	v_add_co_u32_e32 v16, vcc, 0xffffdf80, v16
	s_nop 1
	v_addc_co_u32_e32 v17, vcc, -1, v17, vcc
	global_load_dwordx2 v[16:17], v[16:17], off
	s_or_b64 exec, exec, s[2:3]
	v_add_co_u32_e32 v12, vcc, s21, v12
	s_nop 1
	v_addc_co_u32_e32 v13, vcc, 0, v13, vcc
	global_load_dwordx2 v[102:103], v[12:13], off offset:3072
	v_lshlrev_b64 v[14:15], 5, v[2:3]
	v_lshl_add_u64 v[14:15], s[0:1], 0, v[14:15]
	global_load_dword v104, v[14:15], off
	s_waitcnt vmcnt(0) lgkmcnt(0)
	v_lshlrev_b32_e32 v12, 16, v4
	v_and_b32_e32 v13, 0xffff0000, v4
	v_lshlrev_b32_e32 v4, 16, v5
	v_and_b32_e32 v5, 0xffff0000, v5
	v_pk_add_f32 v[8:9], v[8:9], v[12:13]
	v_pk_add_f32 v[10:11], v[10:11], v[4:5]
	v_mov_b32_e32 v4, v8
	v_mov_b32_e32 v5, v10
	v_mov_b32_e32 v12, v9
	v_mov_b32_e32 v13, v11
	v_pk_add_f32 v[4:5], v[4:5], v[12:13]
	v_add_f32_e32 v0, v4, v5
	s_nop 1
	v_add_f32_dpp v0, v0, v0 quad_perm:[1,0,3,2] row_mask:0xf bank_mask:0xf bound_ctrl:1
	s_nop 1
	v_add_f32_dpp v0, v0, v0 quad_perm:[2,3,0,1] row_mask:0xf bank_mask:0xf bound_ctrl:1
	s_nop 1
	v_add_f32_dpp v0, v0, v0 row_half_mirror row_mask:0xf bank_mask:0xf bound_ctrl:1
	s_nop 1
	v_add_f32_dpp v0, v0, v0 row_mirror row_mask:0xf bank_mask:0xf bound_ctrl:1
	v_fmamk_f32 v11, v0, 0xbc800000, v11
	v_fmamk_f32 v9, v0, 0xbc800000, v9
	v_fmac_f32_e32 v10, 0xbc800000, v0
	v_fmac_f32_e32 v8, 0xbc800000, v0
	v_mul_f32_e32 v0, v9, v9
	v_mul_f32_e32 v4, v11, v11
	v_fmac_f32_e32 v0, v8, v8
	v_fmac_f32_e32 v4, v10, v10
	v_add_f32_e32 v0, v0, v4
	v_mov_b32_e32 v4, 0
	s_nop 0
	v_add_f32_dpp v0, v0, v0 quad_perm:[1,0,3,2] row_mask:0xf bank_mask:0xf bound_ctrl:1
	s_nop 1
	v_add_f32_dpp v0, v0, v0 quad_perm:[2,3,0,1] row_mask:0xf bank_mask:0xf bound_ctrl:1
	s_nop 1
	v_add_f32_dpp v5, v0, v0 row_half_mirror row_mask:0xf bank_mask:0xf bound_ctrl:1
	s_nop 1
	v_mov_b32_dpp v24, v5 row_mirror row_mask:0xf bank_mask:0xf bound_ctrl:1
	v_add_f32_e32 v5, v5, v24
	v_fmamk_f32 v5, v5, 0x3c800000, v214
	v_rsq_f32_e32 v24, v5
	v_lshlrev_b32_e32 v34, 16, v100
	v_and_b32_e32 v35, 0xffff0000, v100
	v_lshlrev_b32_e32 v36, 16, v101
	v_and_b32_e32 v37, 0xffff0000, v101
	v_lshlrev_b32_e32 v5, 16, v16
	v_and_b32_e32 v14, 0xffff0000, v16
	v_lshlrev_b32_e32 v15, 16, v17
	v_and_b32_e32 v16, 0xffff0000, v17
	v_sub_f32_e32 v39, v16, v37
	v_sub_f32_e32 v38, v15, v36
	v_sub_f32_e32 v41, v14, v35
	ds_read_b128 v[14:17], v26 offset:41984
	v_sub_f32_e32 v40, v5, v34
	s_waitcnt lgkmcnt(0)
	v_pk_fma_f32 v[34:35], v[14:15], v[40:41], v[34:35]
	v_pk_fma_f32 v[16:17], v[16:17], v[38:39], v[36:37]
	v_pk_mul_f32 v[40:41], v[10:11], v[24:25] op_sel_hi:[1,0]
	v_pk_mul_f32 v[24:25], v[8:9], v[24:25] op_sel_hi:[1,0]
	ds_read_b128 v[8:11], v26 offset:42240
	ds_read_b128 v[12:15], v26 offset:42496
	s_waitcnt lgkmcnt(0)
	v_pk_fma_f32 v[8:9], v[24:25], v[8:9], v[12:13]
	v_pk_fma_f32 v[10:11], v[40:41], v[10:11], v[14:15]
	v_pk_fma_f32 v[8:9], v[104:105], v[34:35], v[8:9] op_sel_hi:[0,1,1]
	v_lshlrev_b32_e32 v12, 16, v102
	v_mul_f32_e32 v3, 0xbfb8aa3b, v12
	v_exp_f32_e32 v3, v3
	v_and_b32_e32 v13, 0xffff0000, v102
	v_pk_fma_f32 v[10:11], v[104:105], v[16:17], v[10:11] op_sel_hi:[0,1,1]
	v_add_f32_e32 v3, 1.0, v3
	v_rcp_f32_e32 v14, v3
	v_mul_f32_e32 v3, 0xbfb8aa3b, v13
	v_exp_f32_e32 v3, v3
	s_nop 0
	v_add_f32_e32 v3, 1.0, v3
	v_rcp_f32_e32 v15, v3
	s_nop 0
	v_pk_mul_f32 v[12:13], v[14:15], v[12:13]
	s_nop 0
	v_pk_mul_f32 v[8:9], v[12:13], v[8:9]
	v_lshlrev_b32_e32 v12, 16, v103
	v_mul_f32_e32 v3, 0xbfb8aa3b, v12
	v_exp_f32_e32 v3, v3
	v_and_b32_e32 v13, 0xffff0000, v103
	v_cvt_pk_bf16_f32 v8, v8, v9
	v_add_f32_e32 v3, 1.0, v3
	v_rcp_f32_e32 v14, v3
	v_mul_f32_e32 v3, 0xbfb8aa3b, v13
	v_exp_f32_e32 v3, v3
	s_nop 0
	v_add_f32_e32 v3, 1.0, v3
	v_rcp_f32_e32 v15, v3
	s_nop 0
	v_pk_mul_f32 v[12:13], v[14:15], v[12:13]
	s_nop 0
	v_pk_mul_f32 v[10:11], v[12:13], v[10:11]
	s_nop 0
	v_cvt_pk_bf16_f32 v9, v10, v11
	global_store_dwordx2 v[6:7], v[8:9], off offset:1024
	s_add_i32 s6, s6, 4
	v_add_u32_e32 v32, 0x400, v32
	s_cmp_eq_u32 s6, 32
	s_cbranch_scc0 .LBB0_344
	s_branch .LBB0_341

; #define ATT_LOAD(jt) do { ATT_LOADK(jt); ATT_LOADV(jt); } while (0)
; template <int MODE>
; __device__ __forceinline__ void attn_item(const AttnP& p, int b, int h, int qb, LAS unsigned char* lds) {
;     ...
;     ATT_LOAD(jt_max);
;     ATT_STORE(0, jt_max);
;     __syncthreads();
.LBB0_494:
	s_or_b64 exec, exec, s[0:1]
	s_lshl_b32 s0, s5, 2
	v_ashrrev_i32_e32 v4, 3, v50
	s_or_b32 s10, s0, 3
	v_add_u32_e32 v229, s8, v4
	v_lshl_add_u32 v0, s10, 6, v229
	v_mov_b64_e32 v[2:3], s[46:47]
	v_mad_i64_i32 v[2:3], s[0:1], v0, s76, v[2:3]
	v_lshlrev_b32_e32 v0, 3, v50
	v_and_b32_e32 v34, 56, v0
	s_lshl_b32 s0, s9, 1
	s_mov_b32 s1, s93
	v_lshl_add_u64 v[2:3], v[2:3], 0, s[0:1]
	v_lshlrev_b32_e32 v0, 1, v34
	v_lshl_add_u64 v[2:3], v[2:3], 0, v[0:1]
	global_load_dwordx4 v[178:181], v[2:3], off offset:1024
	global_load_dwordx4 v[182:185], v[2:3], off offset:1152
	global_load_dwordx4 v[186:189], v[2:3], off offset:2048
	global_load_dwordx4 v[190:193], v[2:3], off offset:2176
	v_mul_lo_u32 v35, v4, 24
	s_movk_i32 s1, 0x88
	v_mad_u64_u32 v[4:5], s[6:7], v4, s1, v[34:35]
	v_lshlrev_b32_e32 v231, 1, v4
	v_add_lshl_u32 v232, v4, v35, 1
	v_add_u32_e32 v36, 64, v4
	v_add_lshl_u32 v234, v36, v35, 1
	v_add_u32_e32 v37, 0, v231
	v_lshlrev_b32_e32 v233, 1, v36
	v_add_u32_e32 v38, 0, v232
	v_add_u32_e32 v39, 0, v233
	v_lshlrev_b32_e32 v230, 2, v48
	v_and_b32_e32 v41, 16, v50
	s_or_b32 s5, s9, 0x200
	s_or_b32 s6, s9, 0x400
	s_or_b32 s1, s4, 31
	v_mul_u32_u24_e32 v235, 0x110, v49
	s_lshl_b32 s4, s2, 2
	v_mad_i32_i24 v236, v48, -4, v49
	s_lshl_b32 s2, s2, 8
	s_add_i32 s11, s3, 0xffffff01
	v_mov_b32_e32 v208, v1
	v_mov_b32_e32 v209, v1
	s_mov_b32 s12, 0
	s_sub_i32 s13, 64, s4
	s_sub_i32 s14, 0xf80, s2
	s_lshl_b32 s92, s5, 1
	s_lshl_b32 s4, s6, 1
	s_waitcnt vmcnt(0) lgkmcnt(0)
	v_and_b32_e32 v3, 0xffff0000, v181
	v_and_b32_e32 v5, 0xffff0000, v180
	v_and_b32_e32 v7, 0xffff0000, v179
	v_and_b32_e32 v9, 0xffff0000, v178
	v_lshlrev_b32_e32 v2, 16, v181
	v_lshlrev_b32_e32 v4, 16, v180
	v_lshlrev_b32_e32 v6, 16, v179
	v_lshlrev_b32_e32 v8, 16, v178
	v_and_b32_e32 v15, 0xffff0000, v183
	v_and_b32_e32 v17, 0xffff0000, v182
	v_mov_b32_e32 v20, v3
	v_mov_b32_e32 v21, v5
	v_mov_b32_e32 v24, v9
	v_mov_b32_e32 v25, v7
	v_and_b32_e32 v11, 0xffff0000, v185
	v_and_b32_e32 v13, 0xffff0000, v184
	v_lshlrev_b32_e32 v14, 16, v183
	v_lshlrev_b32_e32 v16, 16, v182
	v_mov_b32_e32 v18, v2
	v_mov_b32_e32 v19, v4
	v_mov_b32_e32 v22, v8
	v_mov_b32_e32 v23, v6
	v_mov_b32_e32 v32, v17
	v_mov_b32_e32 v33, v15
	v_pk_mul_f32 v[20:21], v[20:21], v[20:21]
	v_pk_mul_f32 v[24:25], v[24:25], v[24:25]
	v_lshlrev_b32_e32 v10, 16, v185
	v_lshlrev_b32_e32 v12, 16, v184
	v_mov_b32_e32 v28, v11
	v_mov_b32_e32 v29, v13
	v_mov_b32_e32 v30, v16
	v_mov_b32_e32 v31, v14
	v_pk_mul_f32 v[32:33], v[32:33], v[32:33]
	v_pk_fma_f32 v[18:19], v[18:19], v[18:19], v[20:21]
	v_pk_fma_f32 v[20:21], v[22:23], v[22:23], v[24:25]
	v_mov_b32_e32 v26, v10
	v_mov_b32_e32 v27, v12
	v_pk_mul_f32 v[28:29], v[28:29], v[28:29]
	v_pk_fma_f32 v[24:25], v[30:31], v[30:31], v[32:33]
	v_add_f32_e32 v0, v20, v21
	v_pk_fma_f32 v[22:23], v[26:27], v[26:27], v[28:29]
	v_add_f32_e32 v20, v24, v25
	v_add_f32_e32 v0, v19, v0
	v_add_f32_e32 v19, v23, v20
	v_add_f32_e32 v0, v18, v0
	v_add_f32_e32 v18, v22, v19
	s_nop 0
	v_add_f32_dpp v0, v0, v0 quad_perm:[1,0,3,2] row_mask:0xf bank_mask:0xf bound_ctrl:1
	v_add_f32_dpp v18, v18, v18 quad_perm:[1,0,3,2] row_mask:0xf bank_mask:0xf bound_ctrl:1
	s_nop 0
	v_add_f32_dpp v0, v0, v0 quad_perm:[2,3,0,1] row_mask:0xf bank_mask:0xf bound_ctrl:1
	v_add_f32_dpp v18, v18, v18 quad_perm:[2,3,0,1] row_mask:0xf bank_mask:0xf bound_ctrl:1
	s_nop 0
	v_add_f32_dpp v0, v0, v0 row_half_mirror row_mask:0xf bank_mask:0xf bound_ctrl:1
	v_fmamk_f32 v0, v0, 0x3c800000, v211
	v_add_f32_dpp v18, v18, v18 row_half_mirror row_mask:0xf bank_mask:0xf bound_ctrl:1
	v_rsq_f32_e32 v0, v0
	v_fmamk_f32 v18, v18, 0x3c800000, v211
	v_rsq_f32_e32 v18, v18
	v_pk_mul_f32 v[8:9], v[0:1], v[8:9] op_sel_hi:[0,1]
	v_pk_mul_f32 v[6:7], v[0:1], v[6:7] op_sel_hi:[0,1]
	v_pk_mul_f32 v[4:5], v[0:1], v[4:5] op_sel_hi:[0,1]
	v_pk_mul_f32 v[20:21], v[0:1], v[2:3] op_sel_hi:[0,1]
	v_pk_mul_f32 v[16:17], v[18:19], v[16:17] op_sel_hi:[0,1]
	v_pk_mul_f32 v[14:15], v[18:19], v[14:15] op_sel_hi:[0,1]
	v_pk_mul_f32 v[12:13], v[18:19], v[12:13] op_sel_hi:[0,1]
	v_pk_mul_f32 v[10:11], v[18:19], v[10:11] op_sel_hi:[0,1]
	v_cvt_pk_bf16_f32 v2, v8, v9
	v_cvt_pk_bf16_f32 v3, v6, v7
	v_cvt_pk_bf16_f32 v4, v4, v5
	v_cvt_pk_bf16_f32 v5, v20, v21
	v_add_u32_e32 v0, 0, v234
	v_cvt_pk_bf16_f32 v6, v16, v17
	v_cvt_pk_bf16_f32 v7, v14, v15
	v_cvt_pk_bf16_f32 v8, v12, v13
	v_cvt_pk_bf16_f32 v9, v10, v11
	ds_write_b128 v37, v[2:5]
	ds_write_b128 v38, v[186:189] offset:17408
	ds_write_b128 v39, v[6:9]
	ds_write_b128 v0, v[190:193] offset:17408
	v_lshlrev_b32_e32 v0, 2, v51
	s_waitcnt lgkmcnt(0)
	s_barrier
; #define LAS __attribute__((address_space(3)))
; template <int MODE>
; __device__ __forceinline__ void attn_item(const AttnP& p, int b, int h, int qb, LAS unsigned char* lds) {
;     ...
;     f32x16 O[NC][DV / 32];
; #pragma unroll
;     for (int c = 0; c < NC; ++c)
; #pragma unroll
;         for (int d = 0; d < DV / 32; ++d)
; #pragma unroll
;             for (int i = 0; i < 16; ++i) O[c][d][i] = 0.f;
;     float mrun[NC], lsum[NC];
; #pragma unroll
;     for (int c = 0; c < NC; ++c) { mrun[c] = -1e30f; lsum[c] = 0.f; }
;     ...
;     if (MODE == 0) {
;         float gq_ = fabsf(p.qk_gain[lane]), gk_ = fabsf(p.qk_gain[64 + lane]);
;         const LAS float* tab_ = (const LAS float*)(lds + TAB_OFF);
;         float tm_ = fmaxf(fmaxf(fabsf(tab_[lane]), fabsf(tab_[64 + lane])), fmaxf(fabsf(tab_[128 + lane]), fabsf(tab_[192 + lane])));
; #pragma unroll
;         for (int o_ = 1; o_ < 64; o_ <<= 1) { gq_ = fmaxf(gq_, __shfl_xor(gq_, o_)); gk_ = fmaxf(gk_, __shfl_xor(gk_, o_)); tm_ = fmaxf(tm_, __shfl_xor(tm_, o_)); }
;         mfix = 8.0f * gq_ * gk_ * LOG2E * 1.02f + tm_;
;     }
	global_load_dword v35, v0, s[40:41]
	global_load_dword v40, v0, s[40:41] offset:256
	v_add_u32_e32 v0, 0, v0
	v_add_u32_e32 v0, 0x12a00, v0
	ds_read2st64_b32 v[36:37], v0 offset1:1
	ds_read2st64_b32 v[38:39], v0 offset0:2 offset1:3
	v_lshrrev_b32_e32 v18, 2, v50
	v_lshlrev_b32_e32 v19, 2, v50
	v_and_or_b32 v42, v18, 3, v230
	v_and_b32_e32 v43, 12, v19
	s_waitcnt lgkmcnt(0)
	v_max_f32_e64 v39, |v39|, |v39|
	v_max_f32_e64 v38, |v38|, |v38|
	v_max_f32_e32 v38, v38, v39
	v_max3_f32 v36, |v36|, |v37|, v38
	ds_bpermute_b32 v37, v221, v36
	v_mul_u32_u24_e32 v0, 0xa0, v42
	v_or3_b32 v0, v43, v41, v0
	v_lshlrev_b32_e32 v237, 1, v0
	v_mov_b32_e32 v16, v1
	s_waitcnt lgkmcnt(0)
	v_max_f32_e32 v0, v37, v37
	v_max_f32_e32 v0, v36, v0
	ds_bpermute_b32 v38, v222, v0
	v_mov_b32_e32 v17, v1
	v_mov_b32_e32 v2, v1
	v_mov_b32_e32 v3, v1
	v_mov_b32_e32 v4, v1
	s_waitcnt lgkmcnt(0)
	v_max_f32_e32 v38, v38, v38
	v_max_f32_e32 v0, v0, v38
	ds_bpermute_b32 v38, v223, v0
	v_mov_b32_e32 v5, v1
	v_mov_b32_e32 v6, v1
	v_mov_b32_e32 v7, v1
	v_mov_b32_e32 v8, v1
	s_waitcnt lgkmcnt(0)
	v_max_f32_e32 v38, v38, v38
	v_max_f32_e32 v0, v0, v38
	ds_bpermute_b32 v38, v224, v0
	v_mov_b32_e32 v9, v1
	v_mov_b32_e32 v10, v1
	v_mov_b32_e32 v11, v1
	v_mov_b32_e32 v12, v1
	s_waitcnt lgkmcnt(0)
	v_max_f32_e32 v38, v38, v38
	v_max_f32_e32 v0, v0, v38
	ds_bpermute_b32 v38, v225, v0
	v_mov_b32_e32 v13, v1
	v_mov_b32_e32 v14, v1
	v_mov_b32_e32 v15, v1
	v_mov_b64_e32 v[32:33], v[16:17]
	s_waitcnt lgkmcnt(0)
	v_max_f32_e32 v38, v38, v38
	v_max_f32_e32 v38, v0, v38
	v_mov_b64_e32 v[80:81], v[16:17]
	v_mov_b64_e32 v[112:113], v[16:17]
	v_mov_b64_e32 v[64:65], v[16:17]
	v_mov_b64_e32 v[96:97], v[16:17]
	v_mov_b64_e32 v[128:129], v[16:17]
	v_mov_b64_e32 v[30:31], v[14:15]
	v_mov_b64_e32 v[28:29], v[12:13]
	v_mov_b64_e32 v[26:27], v[10:11]
	v_mov_b64_e32 v[24:25], v[8:9]
	v_mov_b64_e32 v[22:23], v[6:7]
	v_mov_b64_e32 v[20:21], v[4:5]
	v_mov_b64_e32 v[18:19], v[2:3]
	v_mov_b64_e32 v[78:79], v[14:15]
	v_mov_b64_e32 v[76:77], v[12:13]
	v_mov_b64_e32 v[74:75], v[10:11]
	v_mov_b64_e32 v[72:73], v[8:9]
	v_mov_b64_e32 v[70:71], v[6:7]
	v_mov_b64_e32 v[68:69], v[4:5]
	v_mov_b64_e32 v[66:67], v[2:3]
	v_mov_b64_e32 v[110:111], v[14:15]
	v_mov_b64_e32 v[108:109], v[12:13]
	v_mov_b64_e32 v[106:107], v[10:11]
	v_mov_b64_e32 v[104:105], v[8:9]
	v_mov_b64_e32 v[102:103], v[6:7]
	v_mov_b64_e32 v[100:101], v[4:5]
	v_mov_b64_e32 v[98:99], v[2:3]
	v_add_u32_e32 v238, 0x2800, v237
	v_add_u32_e32 v239, 0x3c00, v237
	v_add_u32_e32 v240, 0x1400, v237
	v_mov_b64_e32 v[62:63], v[14:15]
	v_mov_b64_e32 v[60:61], v[12:13]
	v_mov_b64_e32 v[58:59], v[10:11]
	s_waitcnt vmcnt(1)
	v_and_b32_e32 v36, 0x7fffffff, v35
	s_waitcnt vmcnt(0)
	v_and_b32_e32 v37, 0x7fffffff, v40
	ds_bpermute_b32 v36, v221, v36
	ds_bpermute_b32 v37, v221, v37
	v_max_f32_e64 v35, |v35|, |v35|
	v_max_f32_e64 v39, |v40|, |v40|
	ds_bpermute_b32 v40, v226, v38
	s_waitcnt lgkmcnt(2)
	v_max_f32_e32 v36, v36, v36
	s_waitcnt lgkmcnt(1)
	v_max_f32_e32 v37, v37, v37
	v_max_f32_e32 v35, v35, v36
	v_max_f32_e32 v36, v39, v37
	ds_bpermute_b32 v37, v222, v35
	ds_bpermute_b32 v39, v222, v36
	v_mov_b64_e32 v[56:57], v[8:9]
	v_mov_b64_e32 v[54:55], v[6:7]
	v_mov_b64_e32 v[52:53], v[4:5]
	s_waitcnt lgkmcnt(1)
	v_max_f32_e32 v37, v37, v37
	s_waitcnt lgkmcnt(0)
	v_max_f32_e32 v39, v39, v39
	v_max_f32_e32 v35, v35, v37
	v_max_f32_e32 v36, v36, v39
	ds_bpermute_b32 v37, v223, v35
	ds_bpermute_b32 v39, v223, v36
	v_mov_b64_e32 v[50:51], v[2:3]
	v_mov_b64_e32 v[94:95], v[14:15]
	v_mov_b64_e32 v[92:93], v[12:13]
	s_waitcnt lgkmcnt(1)
	v_max_f32_e32 v37, v37, v37
	s_waitcnt lgkmcnt(0)
	v_max_f32_e32 v39, v39, v39
	v_max_f32_e32 v35, v35, v37
	v_max_f32_e32 v36, v36, v39
	ds_bpermute_b32 v37, v224, v35
	ds_bpermute_b32 v39, v224, v36
	v_mov_b64_e32 v[90:91], v[10:11]
	v_mov_b64_e32 v[88:89], v[8:9]
	v_mov_b64_e32 v[86:87], v[6:7]
	s_waitcnt lgkmcnt(1)
	v_max_f32_e32 v37, v37, v37
	s_waitcnt lgkmcnt(0)
	v_max_f32_e32 v39, v39, v39
	v_max_f32_e32 v35, v35, v37
	v_max_f32_e32 v36, v36, v39
	ds_bpermute_b32 v37, v225, v35
	ds_bpermute_b32 v39, v225, v36
	v_mov_b64_e32 v[84:85], v[4:5]
	v_mov_b64_e32 v[82:83], v[2:3]
	v_mov_b64_e32 v[126:127], v[14:15]
	s_waitcnt lgkmcnt(1)
	v_max_f32_e32 v0, v37, v37
	s_waitcnt lgkmcnt(0)
	v_max_f32_e32 v37, v39, v39
	v_max_f32_e32 v35, v35, v0
	v_max_f32_e32 v36, v36, v37
	ds_bpermute_b32 v37, v226, v35
	ds_bpermute_b32 v39, v226, v36
	v_lshlrev_b32_e32 v0, 1, v34
	v_max_f32_e32 v34, v40, v40
	v_max_f32_e32 v241, v38, v34
	s_waitcnt lgkmcnt(1)
	v_max_f32_e32 v34, v37, v37
	s_waitcnt lgkmcnt(0)
	v_max_f32_e32 v37, v39, v39
	v_max_f32_e32 v34, v35, v34
	v_max_f32_e32 v35, v36, v37
	v_mul_f32_e32 v34, 0x41000000, v34
	v_mul_f32_e32 v34, v35, v34
	v_mul_f32_e32 v34, 0x3fb8aa3b, v34
	v_fmac_f32_e32 v241, 0x3f828f5c, v34
	v_mov_b64_e32 v[48:49], v[16:17]
	v_mov_b64_e32 v[46:47], v[14:15]
	v_mov_b64_e32 v[44:45], v[12:13]
	v_mov_b64_e32 v[42:43], v[10:11]
	v_mov_b64_e32 v[40:41], v[8:9]
	v_mov_b64_e32 v[38:39], v[6:7]
	v_mov_b64_e32 v[36:37], v[4:5]
	v_mov_b64_e32 v[34:35], v[2:3]
	v_mov_b64_e32 v[124:125], v[12:13]
	v_mov_b64_e32 v[122:123], v[10:11]
	v_mov_b64_e32 v[120:121], v[8:9]
	v_mov_b64_e32 v[118:119], v[6:7]
	v_mov_b64_e32 v[116:117], v[4:5]
	v_mov_b64_e32 v[114:115], v[2:3]
	v_mov_b32_e32 v243, 0x12dfc
	ds_read_b32 v241, v243
	s_waitcnt lgkmcnt(0)
	s_branch .LBB0_496

; __device__ __forceinline__ int crow(int r, int hi) { return (r & 3) + 8 * (r >> 2) + 4 * hi; }
; template <int MODE>
; __device__ __forceinline__ void attn_item(const AttnP& p, int b, int h, int qb, LAS unsigned char* lds) {
;     ...
;                             float binit[16];
; #pragma unroll
;                             for (int i = 0; i < 16; ++i) {
;                                 const int dist = qrow - (kp0 + crow(i, hh));
;                                 binit[i] = (dist < 0) ? -3e38f : (tab[dist > 255 ? 255 : dist] - mfix);
;                             }
; #pragma unroll
;                             for (int c = 0; c < NC; ++c) { ATT_QK(c, binit[i]); ATT_TAIL(c); }
.LBB0_501:
	s_cmpk_lt_i32 s11, 0x80
	s_mov_b64 s[2:3], -1
	s_cbranch_scc0 .Lfar_tile
	v_add_u32_e32 v146, s11, v236
	v_mov_b32_e32 v148, 0xff61b1e6
	v_add_u32_e32 v149, 31, v146
	s_mov_b32 s2, 0x12a10
	v_lshl_add_u32 v147, v146, 2, s2
	ds_read2_b32 v[130:131], v147 offset0:27 offset1:26
	ds_read2_b32 v[132:133], v147 offset0:25 offset1:24
	ds_read2_b32 v[134:135], v147 offset0:19 offset1:18
	ds_read2_b32 v[136:137], v147 offset0:17 offset1:16
	ds_read2_b32 v[138:139], v147 offset0:11 offset1:10
	ds_read2_b32 v[140:141], v147 offset0:9 offset1:8
	ds_read2_b32 v[142:143], v147 offset0:3 offset1:2
	ds_read2_b32 v[144:145], v147 offset0:1 offset1:0
	s_waitcnt lgkmcnt(0)
	v_cmp_le_i32_e64 vcc, 0, v149
	v_sub_f32_e32 v130, v130, v241
	v_cmp_le_i32_e64 s[2:3], 1, v149
	v_sub_f32_e32 v131, v131, v241
	v_cndmask_b32_e64 v130, v148, v130, vcc
	v_cmp_le_i32_e64 vcc, 2, v149
	v_sub_f32_e32 v132, v132, v241
	v_cndmask_b32_e64 v131, v148, v131, s[2:3]
	v_cmp_le_i32_e64 s[2:3], 3, v149
	v_sub_f32_e32 v133, v133, v241
	v_cndmask_b32_e64 v132, v148, v132, vcc
	v_cmp_le_i32_e64 vcc, 8, v149
	v_sub_f32_e32 v134, v134, v241
	v_cndmask_b32_e64 v133, v148, v133, s[2:3]
	v_cmp_le_i32_e64 s[2:3], 9, v149
	v_sub_f32_e32 v135, v135, v241
	v_cndmask_b32_e64 v134, v148, v134, vcc
	v_cmp_le_i32_e64 vcc, 10, v149
	v_sub_f32_e32 v136, v136, v241
	v_cndmask_b32_e64 v135, v148, v135, s[2:3]
	v_cmp_le_i32_e64 s[2:3], 11, v149
	v_sub_f32_e32 v137, v137, v241
	v_cndmask_b32_e64 v136, v148, v136, vcc
	v_cmp_le_i32_e64 vcc, 16, v149
	v_sub_f32_e32 v138, v138, v241
	v_cndmask_b32_e64 v137, v148, v137, s[2:3]
	v_cmp_le_i32_e64 s[2:3], 17, v149
	v_sub_f32_e32 v139, v139, v241
	v_cndmask_b32_e64 v138, v148, v138, vcc
	v_cmp_le_i32_e64 vcc, 18, v149
	v_sub_f32_e32 v140, v140, v241
	v_cndmask_b32_e64 v139, v148, v139, s[2:3]
	v_cmp_le_i32_e64 s[2:3], 19, v149
	v_sub_f32_e32 v141, v141, v241
	v_cndmask_b32_e64 v140, v148, v140, vcc
	v_cmp_le_i32_e64 vcc, 24, v149
	v_sub_f32_e32 v142, v142, v241
	v_cndmask_b32_e64 v141, v148, v141, s[2:3]
	v_cmp_le_i32_e64 s[2:3], 25, v149
	v_sub_f32_e32 v143, v143, v241
	v_cndmask_b32_e64 v142, v148, v142, vcc
	v_cmp_le_i32_e64 vcc, 26, v149
	v_sub_f32_e32 v144, v144, v241
	v_cndmask_b32_e64 v143, v148, v143, s[2:3]
	v_cmp_le_i32_e64 s[2:3], 27, v149
	v_sub_f32_e32 v145, v145, v241
	s_nop 0
	v_cndmask_b32_e64 v144, v148, v144, vcc
	v_cndmask_b32_e64 v145, v148, v145, s[2:3]
	v_add_u32_e32 v243, v242, v235
	ds_read_b128 v[244:247], v243 offset:8704
	ds_read_b128 v[248:251], v243 offset:8736
	s_mov_b64 s[2:3], 0
	s_waitcnt lgkmcnt(0)
	v_mfma_f32_32x32x16_bf16 v[146:161], v[244:247], v[162:165], v[130:145]
	ds_read_b128 v[244:247], v243 offset:8768
	v_mfma_f32_32x32x16_bf16 v[146:161], v[248:251], v[166:169], v[146:161]
	s_waitcnt lgkmcnt(0)
	v_mfma_f32_32x32x16_bf16 v[146:161], v[244:247], v[170:173], v[146:161]
	ds_read_b128 v[244:247], v243 offset:8800
	s_waitcnt lgkmcnt(0)
	v_mfma_f32_32x32x16_bf16 v[146:161], v[244:247], v[174:177], v[146:161]
	s_nop 11
	v_exp_f32_e32 v146, v146
	v_exp_f32_e32 v147, v147
	v_exp_f32_e32 v148, v148
	v_exp_f32_e32 v149, v149
	v_add_f32_e32 v244, 0, v146
	v_exp_f32_e32 v245, v150
	v_add_f32_e32 v244, v147, v244
	v_add_f32_e32 v244, v148, v244
	v_add_f32_e32 v244, v149, v244
	v_add_f32_e32 v150, v245, v244
	v_exp_f32_e32 v244, v151
	v_exp_f32_e32 v246, v152
	v_exp_f32_e32 v153, v153
	v_exp_f32_e32 v154, v154
	v_add_f32_e32 v150, v244, v150
	v_exp_f32_e32 v247, v155
	v_add_f32_e32 v150, v246, v150
	v_exp_f32_e32 v156, v156
	v_add_f32_e32 v150, v153, v150
	v_exp_f32_e32 v157, v157
	v_add_f32_e32 v150, v154, v150
	v_exp_f32_e32 v158, v158
	v_add_f32_e32 v150, v247, v150
	v_exp_f32_e32 v159, v159
	v_add_f32_e32 v150, v156, v150
	v_exp_f32_e32 v160, v160
	v_add_f32_e32 v150, v157, v150
	v_exp_f32_e32 v161, v161
	v_add_f32_e32 v150, v158, v150
	v_add_f32_e32 v150, v159, v150
	v_add_f32_e32 v150, v160, v150
	v_add_f32_e32 v155, v161, v150
	v_cvt_pk_bf16_f32 v150, v146, v147
	v_cvt_pk_bf16_f32 v151, v148, v149
	v_cvt_pk_bf16_f32 v152, v245, v244
	v_cvt_pk_bf16_f32 v153, v246, v153
	v_cvt_pk_bf16_f32 v146, v154, v247
	v_cvt_pk_bf16_f32 v147, v156, v157
	v_cvt_pk_bf16_f32 v148, v158, v159
	ds_read_b128 v[156:159], v243 offset:8832
	ds_read_b128 v[244:247], v207 offset:4096
	s_waitcnt lgkmcnt(0)
	v_mfma_f32_32x32x16_bf16 v[130:145], v[156:159], v[244:247], v[130:145]
	ds_read_b128 v[156:159], v243 offset:8864
	ds_read_b128 v[244:247], v207 offset:5120
	v_cvt_pk_bf16_f32 v149, v160, v161
	s_waitcnt lgkmcnt(0)
	v_mfma_f32_32x32x16_bf16 v[130:145], v[156:159], v[244:247], v[130:145]
	ds_read_b128 v[156:159], v243 offset:8896
	ds_read_b128 v[244:247], v207 offset:6144
	s_waitcnt lgkmcnt(0)
	v_mfma_f32_32x32x16_bf16 v[130:145], v[156:159], v[244:247], v[130:145]
	ds_read_b128 v[156:159], v243 offset:8928
	ds_read_b128 v[244:247], v207 offset:7168
	s_waitcnt lgkmcnt(0)
	v_mfma_f32_32x32x16_bf16 v[130:145], v[156:159], v[244:247], v[130:145]

; __device__ __forceinline__ int crow(int r, int hi) { return (r & 3) + 8 * (r >> 2) + 4 * hi; }
; template <int MODE>
; __device__ __forceinline__ void attn_item(const AttnP& p, int b, int h, int qb, LAS unsigned char* lds) {
;     ...
;                             float binit[16];
; #pragma unroll
;                             for (int i = 0; i < 16; ++i) {
;                                 const int dist = qrow - (kp0 + crow(i, hh));
;                                 binit[i] = (dist < 0) ? -3e38f : (tab[dist > 255 ? 255 : dist] - mfix);
;                             }
; #pragma unroll
;                             for (int c = 0; c < NC; ++c) { ATT_QK(c, binit[i]); ATT_TAIL(c); }
.LBB0_538:
	s_add_i32 s2, s11, 32
	s_cmpk_gt_i32 s2, 0x7f
	s_mov_b64 s[2:3], -1
	s_cbranch_scc1 .LBB0_572
	v_add_u32_e32 v146, s11, v236
	v_mov_b32_e32 v148, 0xff61b1e6
	v_add_u32_e32 v149, 63, v146
	s_mov_b32 s2, 0x12a90
	v_lshl_add_u32 v147, v146, 2, s2
	ds_read2_b32 v[130:131], v147 offset0:27 offset1:26
	ds_read2_b32 v[132:133], v147 offset0:25 offset1:24
	ds_read2_b32 v[134:135], v147 offset0:19 offset1:18
	ds_read2_b32 v[136:137], v147 offset0:17 offset1:16
	ds_read2_b32 v[138:139], v147 offset0:11 offset1:10
	ds_read2_b32 v[140:141], v147 offset0:9 offset1:8
	ds_read2_b32 v[142:143], v147 offset0:3 offset1:2
	ds_read2_b32 v[144:145], v147 offset0:1 offset1:0
	s_waitcnt lgkmcnt(0)
	v_cmp_le_i32_e64 vcc, 0, v149
	v_sub_f32_e32 v130, v130, v241
	v_cmp_le_i32_e64 s[2:3], 1, v149
	v_sub_f32_e32 v131, v131, v241
	v_cndmask_b32_e64 v130, v148, v130, vcc
	v_cmp_le_i32_e64 vcc, 2, v149
	v_sub_f32_e32 v132, v132, v241
	v_cndmask_b32_e64 v131, v148, v131, s[2:3]
	v_cmp_le_i32_e64 s[2:3], 3, v149
	v_sub_f32_e32 v133, v133, v241
	v_cndmask_b32_e64 v132, v148, v132, vcc
	v_cmp_le_i32_e64 vcc, 8, v149
	v_sub_f32_e32 v134, v134, v241
	v_cndmask_b32_e64 v133, v148, v133, s[2:3]
	v_cmp_le_i32_e64 s[2:3], 9, v149
	v_sub_f32_e32 v135, v135, v241
	v_cndmask_b32_e64 v134, v148, v134, vcc
	v_cmp_le_i32_e64 vcc, 10, v149
	v_sub_f32_e32 v136, v136, v241
	v_cndmask_b32_e64 v135, v148, v135, s[2:3]
	v_cmp_le_i32_e64 s[2:3], 11, v149
	v_sub_f32_e32 v137, v137, v241
	v_cndmask_b32_e64 v136, v148, v136, vcc
	v_cmp_le_i32_e64 vcc, 16, v149
	v_sub_f32_e32 v138, v138, v241
	v_cndmask_b32_e64 v137, v148, v137, s[2:3]
	v_cmp_le_i32_e64 s[2:3], 17, v149
	v_sub_f32_e32 v139, v139, v241
	v_cndmask_b32_e64 v138, v148, v138, vcc
	v_cmp_le_i32_e64 vcc, 18, v149
	v_sub_f32_e32 v140, v140, v241
	v_cndmask_b32_e64 v139, v148, v139, s[2:3]
	v_cmp_le_i32_e64 s[2:3], 19, v149
	v_sub_f32_e32 v141, v141, v241
	v_cndmask_b32_e64 v140, v148, v140, vcc
	v_cmp_le_i32_e64 vcc, 24, v149
	v_sub_f32_e32 v142, v142, v241
	v_cndmask_b32_e64 v141, v148, v141, s[2:3]
	v_cmp_le_i32_e64 s[2:3], 25, v149
	v_sub_f32_e32 v143, v143, v241
	v_cndmask_b32_e64 v142, v148, v142, vcc
	v_cmp_le_i32_e64 vcc, 26, v149
	v_sub_f32_e32 v144, v144, v241
	v_cndmask_b32_e64 v143, v148, v143, s[2:3]
	v_cmp_le_i32_e64 s[2:3], 27, v149
	v_sub_f32_e32 v145, v145, v241
	s_nop 0
	v_cndmask_b32_e64 v144, v148, v144, vcc
	v_cndmask_b32_e64 v145, v148, v145, s[2:3]
	v_add_u32_e32 v243, v242, v235
	ds_read_b128 v[244:247], v243
	ds_read_b128 v[248:251], v243 offset:32
	s_mov_b64 s[2:3], 0
	s_waitcnt lgkmcnt(0)
	v_mfma_f32_32x32x16_bf16 v[146:161], v[244:247], v[162:165], v[130:145]
	ds_read_b128 v[244:247], v243 offset:64
	v_mfma_f32_32x32x16_bf16 v[146:161], v[248:251], v[166:169], v[146:161]
	s_waitcnt lgkmcnt(0)
	v_mfma_f32_32x32x16_bf16 v[146:161], v[244:247], v[170:173], v[146:161]
	ds_read_b128 v[244:247], v243 offset:96
	s_waitcnt lgkmcnt(0)
	v_mfma_f32_32x32x16_bf16 v[146:161], v[244:247], v[174:177], v[146:161]
	s_nop 11
	v_exp_f32_e32 v146, v146
	v_exp_f32_e32 v147, v147
	v_exp_f32_e32 v148, v148
	v_exp_f32_e32 v149, v149
	v_add_f32_e32 v244, 0, v146
	v_exp_f32_e32 v245, v150
	v_add_f32_e32 v244, v147, v244
	v_add_f32_e32 v244, v148, v244
	v_add_f32_e32 v244, v149, v244
	v_add_f32_e32 v150, v245, v244
	v_exp_f32_e32 v244, v151
	v_exp_f32_e32 v246, v152
	v_exp_f32_e32 v153, v153
	v_exp_f32_e32 v154, v154
	v_add_f32_e32 v150, v244, v150
	v_exp_f32_e32 v247, v155
	v_add_f32_e32 v150, v246, v150
	v_exp_f32_e32 v156, v156
	v_add_f32_e32 v150, v153, v150
	v_exp_f32_e32 v157, v157
	v_add_f32_e32 v150, v154, v150
	v_exp_f32_e32 v158, v158
	v_add_f32_e32 v150, v247, v150
	v_exp_f32_e32 v159, v159
	v_add_f32_e32 v150, v156, v150
	v_exp_f32_e32 v160, v160
	v_add_f32_e32 v150, v157, v150
	v_exp_f32_e32 v161, v161
	v_add_f32_e32 v150, v158, v150
	v_add_f32_e32 v150, v159, v150
	v_add_f32_e32 v150, v160, v150
	v_add_f32_e32 v155, v161, v150
	v_cvt_pk_bf16_f32 v150, v146, v147
	v_cvt_pk_bf16_f32 v151, v148, v149
	v_cvt_pk_bf16_f32 v152, v245, v244
	v_cvt_pk_bf16_f32 v153, v246, v153
	v_cvt_pk_bf16_f32 v146, v154, v247
	v_cvt_pk_bf16_f32 v147, v156, v157
	v_cvt_pk_bf16_f32 v148, v158, v159
	ds_read_b128 v[156:159], v243 offset:128
	ds_read_b128 v[244:247], v207 offset:4096
	s_waitcnt lgkmcnt(0)
	v_mfma_f32_32x32x16_bf16 v[130:145], v[156:159], v[244:247], v[130:145]
	ds_read_b128 v[156:159], v243 offset:160
	ds_read_b128 v[244:247], v207 offset:5120
	v_cvt_pk_bf16_f32 v149, v160, v161
	s_waitcnt lgkmcnt(0)
	v_mfma_f32_32x32x16_bf16 v[130:145], v[156:159], v[244:247], v[130:145]
	ds_read_b128 v[156:159], v243 offset:192
	ds_read_b128 v[244:247], v207 offset:6144
	s_waitcnt lgkmcnt(0)
	v_mfma_f32_32x32x16_bf16 v[130:145], v[156:159], v[244:247], v[130:145]
	ds_read_b128 v[156:159], v243 offset:224
	ds_read_b128 v[244:247], v207 offset:7168
	s_waitcnt lgkmcnt(0)
	v_mfma_f32_32x32x16_bf16 v[130:145], v[156:159], v[244:247], v[130:145]
